# grid barrier: leaders no longer bump the unused per-XCD generation; down-proj to up-proj seam (pure write-after-read ordering) drops its L2 writeback and invalidates
# baseline (speedup 1.0000x reference)
.LBB0_104:
	s_or_b64 exec, exec, s[8:9]
	s_mov_b64 s[8:9], exec
	v_mbcnt_lo_u32_b32 v0, s8, 0
	v_mbcnt_hi_u32_b32 v0, s9, v0
	v_cmp_eq_u32_e32 vcc, 0, v0
	s_waitcnt vmcnt(0)
	buffer_inv sc1
	s_and_saveexec_b64 s[10:11], vcc
	s_cbranch_execz .LBB0_106
	s_bcnt1_i32_b64 s3, s[8:9]
	v_mov_b32_e32 v0, 0x2000
	v_mov_b32_e32 v1, s3

.LBB0_505:
	s_or_b64 exec, exec, s[6:7]
	s_mov_b64 s[6:7], exec
	v_mbcnt_lo_u32_b32 v0, s6, 0
	v_mbcnt_hi_u32_b32 v0, s7, v0
	v_cmp_eq_u32_e32 vcc, 0, v0
	s_waitcnt vmcnt(0)
	buffer_inv sc1
	s_and_saveexec_b64 s[8:9], vcc
	s_cbranch_execz .LBB0_507
	s_bcnt1_i32_b64 s3, s[6:7]
	v_mov_b32_e32 v0, 0x2000
	v_mov_b32_e32 v1, s3

.LBB0_592:
	s_or_b64 exec, exec, s[10:11]
	s_mov_b64 s[10:11], exec
	v_mbcnt_lo_u32_b32 v0, s10, 0
	v_mbcnt_hi_u32_b32 v0, s11, v0
	v_cmp_eq_u32_e32 vcc, 0, v0
	s_waitcnt vmcnt(0)
	buffer_inv sc1
	s_and_saveexec_b64 s[24:25], vcc
	s_cbranch_execz .LBB0_594
	s_bcnt1_i32_b64 s10, s[10:11]
	v_mov_b32_e32 v0, s10
	v_readlane_b32 s10, v254, 60
	v_readlane_b32 s11, v254, 61
	s_nop 4

.LBB0_660:
	s_or_b64 exec, exec, s[24:25]
	s_waitcnt vmcnt(0)
	s_waitcnt vmcnt(0)
.LBB0_661:
	s_andn2_saveexec_b64 s[10:11], s[10:11]
	s_cbranch_execz .LBB0_512
	s_mov_b64 s[10:11], exec
	s_waitcnt lgkmcnt(0)
	s_waitcnt vmcnt(0)
	v_mbcnt_lo_u32_b32 v1, s10, 0
	v_mbcnt_hi_u32_b32 v1, s11, v1
	v_cmp_eq_u32_e32 vcc, 0, v1
	s_and_saveexec_b64 s[24:25], vcc
	s_cbranch_execz .LBB0_664
	s_bcnt1_i32_b64 s8, s[10:11]
	v_readlane_b32 s10, v255, 34
	v_mov_b32_e32 v2, s8
	v_readlane_b32 s11, v255, 35
	s_nop 4
	global_atomic_add v2, v129, v2, s[10:11] sc0

.LBB0_678:
	s_or_b64 exec, exec, s[10:11]
	s_mov_b64 s[10:11], exec
	v_mbcnt_lo_u32_b32 v0, s10, 0
	v_mbcnt_hi_u32_b32 v0, s11, v0
	v_cmp_eq_u32_e32 vcc, 0, v0
	s_waitcnt vmcnt(0)
	s_and_saveexec_b64 s[24:25], vcc
	s_cbranch_execz .LBB0_511
	s_bcnt1_i32_b64 s8, s[10:11]
	v_readlane_b32 s10, v254, 60
	v_mov_b32_e32 v0, s8
	v_readlane_b32 s11, v254, 61
	s_nop 4
	s_branch .LBB0_511
